# attention steady loop: PV MFMAs 1-3 interleaved with the row-max chain, V-tile DMA issue moved into the first PV gaps, K/V DMA saddr addressing
# speedup vs baseline: 1.0141x; 1.0046x over previous
.LBB0_300:
	s_lshl_b32 s0, s0, 1
	v_add_u32_e32 v0, s0, v248
	ds_read_b64_tr_b16 v[2:3], v0 offset:24576
	ds_read_b64_tr_b16 v[4:5], v0 offset:25088
	s_waitcnt lgkmcnt(9)
	v_mfma_f32_32x32x16_bf16 v[144:159], v[220:223], v[188:191], v[80:95]
	v_add_f32_e32 v6, v112, v113
	v_add_f32_e32 v6, v114, v6
	v_add_f32_e32 v6, v115, v6
	v_add_f32_e32 v6, v116, v6
	v_add_f32_e32 v10, v117, v6
	v_cvt_pk_bf16_f32 v180, v112, v113
	v_cvt_pk_bf16_f32 v181, v114, v115
	ds_read_b64_tr_b16 v[6:7], v0 offset:28672
	ds_read_b64_tr_b16 v[8:9], v0 offset:29184
	s_waitcnt lgkmcnt(10)
	v_mfma_f32_32x32x16_bf16 v[128:143], v[216:219], v[188:191], v[80:95]
	v_add_f32_e32 v10, v118, v10
	v_add_f32_e32 v10, v119, v10
	v_add_f32_e32 v10, v120, v10
	v_add_f32_e32 v14, v121, v10
	v_cvt_pk_bf16_f32 v182, v116, v117
	v_cvt_pk_bf16_f32 v183, v118, v119
	ds_read_b64_tr_b16 v[10:11], v0 offset:25600
	ds_read_b64_tr_b16 v[12:13], v0 offset:26112
	s_waitcnt lgkmcnt(11)
	v_mfma_f32_32x32x16_bf16 v[144:159], v[212:215], v[184:187], v[144:159]
	v_add_f32_e32 v14, v122, v14
	v_add_f32_e32 v14, v123, v14
	v_add_f32_e32 v14, v124, v14
	v_add_f32_e32 v14, v125, v14
	v_cvt_pk_bf16_f32 v172, v120, v121
	v_cvt_pk_bf16_f32 v173, v122, v123
	ds_read_b64_tr_b16 v[112:113], v0 offset:29696
	ds_read_b64_tr_b16 v[114:115], v0 offset:30208
	s_waitcnt lgkmcnt(12)
	v_mfma_f32_32x32x16_bf16 v[128:143], v[208:211], v[184:187], v[128:143]
	v_add_f32_e32 v14, v126, v14
	v_add_f32_e32 v14, v127, v14
	v_add_f32_e32 v14, v96, v14
	v_add_f32_e32 v14, v97, v14
	v_cvt_pk_bf16_f32 v174, v124, v125
	v_cvt_pk_bf16_f32 v175, v126, v127
	ds_read_b64_tr_b16 v[116:117], v0 offset:26624
	ds_read_b64_tr_b16 v[118:119], v0 offset:27136
	s_waitcnt lgkmcnt(13)
	v_mfma_f32_32x32x16_bf16 v[144:159], v[204:207], v[176:179], v[144:159]
	v_add_f32_e32 v14, v98, v14
	v_add_f32_e32 v14, v99, v14
	v_add_f32_e32 v14, v100, v14
	v_add_f32_e32 v14, v101, v14
	v_cvt_pk_bf16_f32 v164, v96, v97
	v_cvt_pk_bf16_f32 v165, v98, v99
	ds_read_b64_tr_b16 v[96:97], v0 offset:30720
	ds_read_b64_tr_b16 v[98:99], v0 offset:31232
	s_waitcnt lgkmcnt(14)
	v_mfma_f32_32x32x16_bf16 v[128:143], v[200:203], v[176:179], v[128:143]
	v_add_f32_e32 v14, v102, v14
	v_add_f32_e32 v14, v103, v14
	v_add_f32_e32 v14, v104, v14
	v_add_f32_e32 v14, v105, v14
	v_cvt_pk_bf16_f32 v166, v100, v101
	v_cvt_pk_bf16_f32 v167, v102, v103
	ds_read_b64_tr_b16 v[100:101], v0 offset:27648
	ds_read_b64_tr_b16 v[102:103], v0 offset:28160
	s_waitcnt lgkmcnt(14)
	v_mfma_f32_32x32x16_bf16 v[144:159], v[196:199], v[168:171], v[144:159]
	v_add_f32_e32 v14, v106, v14
	v_add_f32_e32 v14, v107, v14
	v_add_f32_e32 v14, v108, v14
	v_add_f32_e32 v14, v109, v14
	v_cvt_pk_bf16_f32 v160, v104, v105
	v_cvt_pk_bf16_f32 v161, v106, v107
	ds_read_b64_tr_b16 v[104:105], v0 offset:31744
	ds_read_b64_tr_b16 v[106:107], v0 offset:32256
	v_mfma_f32_32x32x16_bf16 v[128:143], v[192:195], v[168:171], v[128:143]
	v_add_f32_e32 v14, v110, v14
	v_add_f32_e32 v14, v111, v14
	v_add_f32_e32 v214, v250, v14
	v_cvt_pk_bf16_f32 v162, v108, v109
	v_cvt_pk_bf16_f32 v163, v110, v111
	s_add_i32 s0, s38, s46
	s_mov_b32 s1, m0
	s_mov_b32 m0, s0
	s_nop 0
	global_load_lds_dwordx4 v253, s[98:99]
	s_mov_b32 m0, s1
	s_waitcnt lgkmcnt(14)
	v_mfma_f32_32x32x16_bf16 v[16:31], v[180:183], v[2:5], v[16:31]
	v_max_f32_e32 v108, v144, v145
	v_max3_f32 v109, v146, v147, v129
	v_max3_f32 v108, v108, v128, v130
	v_max3_f32 v108, v108, v131, v148
	v_max3_f32 v109, v109, v150, v151
	v_max3_f32 v108, v108, v149, v132
	s_waitcnt lgkmcnt(12)
	v_mfma_f32_32x32x16_bf16 v[32:47], v[180:183], v[6:9], v[32:47]
	v_max3_f32 v109, v109, v134, v135
	v_max3_f32 v108, v108, v133, v152
	v_max3_f32 v109, v109, v154, v155
	v_max3_f32 v108, v108, v153, v136
	v_max3_f32 v109, v109, v138, v139
	v_max3_f32 v108, v108, v137, v156
	s_waitcnt lgkmcnt(10)
	v_mfma_f32_32x32x16_bf16 v[16:31], v[172:175], v[10:13], v[16:31]
	v_max3_f32 v109, v109, v158, v159
	v_max3_f32 v108, v108, v157, v140
	v_max3_f32 v109, v109, v142, v143
	v_max3_f32 v108, v108, v141, v109
	v_mov_b32_e32 v109, v108
	s_nop 1
	v_permlane32_swap_b32_e32 v108, v109
	v_max_f32_e32 v108, v108, v109
	v_cmp_lt_f32_e32 vcc, s25, v108
	s_cmp_lg_u64 vcc, 0
	s_cselect_b64 s[78:79], -1, 0
	s_cbranch_vccnz .LBB0_308
.LBB0_301:
	v_exp_f32_e32 v144, v144
	v_exp_f32_e32 v145, v145
	ds_read_b64_tr_b16 v[2:3], v0 offset:32768
	ds_read_b64_tr_b16 v[4:5], v0 offset:33280
	v_exp_f32_e32 v146, v146
	v_exp_f32_e32 v147, v147
	ds_read_b64_tr_b16 v[6:7], v0 offset:36864
	ds_read_b64_tr_b16 v[8:9], v0 offset:37376
	s_lshl_b32 s0, s19, 1
	s_add_i32 s0, s0, s47
	s_mov_b32 s1, m0
	s_mov_b32 m0, s0
	s_nop 0
	global_load_lds_dwordx4 v255, s[100:101]
	s_mov_b32 m0, s1
	v_exp_f32_e32 v148, v148
	v_exp_f32_e32 v149, v149
	ds_read_b64_tr_b16 v[10:11], v0 offset:33792
	ds_read_b64_tr_b16 v[12:13], v0 offset:34304
	s_addk_i32 s0, 0x1f80
	s_mov_b32 s1, m0
	s_mov_b32 m0, s0
	s_nop 0
	global_load_lds_dwordx4 v255, s[100:101] offset:128
	s_mov_b32 m0, s1
	s_add_u32 s98, s98, 0x20000
	s_addc_u32 s99, s99, 0
	s_add_u32 s100, s100, 0x20000
	s_addc_u32 s101, s101, 0
	s_waitcnt lgkmcnt(14)
	v_mfma_f32_32x32x16_bf16 v[32:47], v[172:175], v[112:115], v[32:47]
	v_exp_f32_e32 v150, v150
	v_exp_f32_e32 v151, v151
	ds_read_b64_tr_b16 v[108:109], v0 offset:37888
	ds_read_b64_tr_b16 v[110:111], v0 offset:38400
	s_waitcnt lgkmcnt(14)
	v_mfma_f32_32x32x16_bf16 v[16:31], v[164:167], v[116:119], v[16:31]
	v_exp_f32_e32 v152, v152
	v_exp_f32_e32 v153, v153
	ds_read_b64_tr_b16 v[112:113], v0 offset:34816
	ds_read_b64_tr_b16 v[114:115], v0 offset:35328
	s_waitcnt lgkmcnt(14)
	v_mfma_f32_32x32x16_bf16 v[32:47], v[164:167], v[96:99], v[32:47]
	v_exp_f32_e32 v154, v154
	v_exp_f32_e32 v155, v155
	ds_read_b64_tr_b16 v[116:117], v0 offset:38912
	ds_read_b64_tr_b16 v[118:119], v0 offset:39424
	s_waitcnt lgkmcnt(14)
	v_mfma_f32_32x32x16_bf16 v[16:31], v[160:163], v[100:103], v[16:31]
	v_exp_f32_e32 v156, v156
	v_exp_f32_e32 v157, v157
	ds_read_b64_tr_b16 v[100:101], v0 offset:35840
	ds_read_b64_tr_b16 v[102:103], v0 offset:36352
	s_waitcnt lgkmcnt(14)
	v_mfma_f32_32x32x16_bf16 v[32:47], v[160:163], v[104:107], v[32:47]
	v_exp_f32_e32 v158, v158
	v_exp_f32_e32 v159, v159
	ds_read_b64_tr_b16 v[104:105], v0 offset:39936
	ds_read_b64_tr_b16 v[106:107], v0 offset:40448
	s_waitcnt lgkmcnt(14)
	v_mfma_f32_32x32x16_bf16 v[48:63], v[180:183], v[2:5], v[48:63]
	v_exp_f32_e32 v128, v128
	v_exp_f32_e32 v129, v129
	s_waitcnt lgkmcnt(12)
	v_mfma_f32_32x32x16_bf16 v[64:79], v[180:183], v[6:9], v[64:79]
	v_exp_f32_e32 v130, v130
	v_exp_f32_e32 v131, v131
	v_add_u32_e32 v0, s19, v247
	ds_read_b128 v[96:99], v0
	ds_read_b128 v[204:207], v0 offset:512
	s_waitcnt lgkmcnt(12)
	v_mfma_f32_32x32x16_bf16 v[48:63], v[172:175], v[10:13], v[48:63]
	v_exp_f32_e32 v132, v132
	v_exp_f32_e32 v133, v133
	ds_read_b128 v[208:211], v0 offset:2048
	ds_read_b128 v[200:203], v0 offset:2560
	s_waitcnt lgkmcnt(12)
	v_mfma_f32_32x32x16_bf16 v[64:79], v[172:175], v[108:111], v[64:79]
	v_exp_f32_e32 v134, v134
	v_exp_f32_e32 v135, v135
	ds_read_b128 v[196:199], v0 offset:4096
	ds_read_b128 v[10:13], v0 offset:4608
	s_waitcnt lgkmcnt(12)
	v_mfma_f32_32x32x16_bf16 v[48:63], v[164:167], v[112:115], v[48:63]
	v_exp_f32_e32 v136, v136
	v_exp_f32_e32 v137, v137
	ds_read_b128 v[6:9], v0 offset:6144
	ds_read_b128 v[2:5], v0 offset:6656
	s_waitcnt lgkmcnt(12)
	v_mfma_f32_32x32x16_bf16 v[64:79], v[164:167], v[116:119], v[64:79]
	v_exp_f32_e32 v138, v138
	v_exp_f32_e32 v139, v139
	s_waitcnt lgkmcnt(10)
	v_mfma_f32_32x32x16_bf16 v[48:63], v[160:163], v[100:103], v[48:63]
	v_exp_f32_e32 v140, v140
	v_exp_f32_e32 v141, v141
	s_waitcnt lgkmcnt(8)
	v_mfma_f32_32x32x16_bf16 v[64:79], v[160:163], v[104:107], v[64:79]
	v_exp_f32_e32 v142, v142
	v_exp_f32_e32 v143, v143
	s_waitcnt vmcnt(3) lgkmcnt(0)
	s_barrier
	s_andn2_b64 vcc, exec, s[78:79]
	v_add_u32_e32 v0, s45, v249
	s_cbranch_vccnz .LBB0_303
	s_waitcnt lgkmcnt(0)
	ds_read_b128 v[100:103], v0 offset:96
	ds_read_b128 v[104:107], v0 offset:64
	ds_read_b128 v[108:111], v0 offset:32
	ds_read_b128 v[112:115], v0
	s_waitcnt lgkmcnt(3)
	v_pk_mul_f32 v[28:29], v[28:29], v[100:101]
	s_waitcnt lgkmcnt(2)
	v_pk_mul_f32 v[24:25], v[24:25], v[104:105]
	s_waitcnt lgkmcnt(1)
	v_pk_mul_f32 v[20:21], v[20:21], v[108:109]
	v_pk_mul_f32 v[30:31], v[30:31], v[102:103]
	v_pk_mul_f32 v[26:27], v[26:27], v[106:107]
	v_pk_mul_f32 v[22:23], v[22:23], v[110:111]
	s_waitcnt lgkmcnt(0)
	v_pk_mul_f32 v[18:19], v[18:19], v[114:115]
	v_pk_mul_f32 v[16:17], v[16:17], v[112:113]
	v_pk_mul_f32 v[44:45], v[44:45], v[100:101]
	v_pk_mul_f32 v[40:41], v[40:41], v[104:105]
	v_pk_mul_f32 v[36:37], v[36:37], v[108:109]
	v_pk_mul_f32 v[46:47], v[46:47], v[102:103]
	v_pk_mul_f32 v[42:43], v[42:43], v[106:107]
	v_pk_mul_f32 v[38:39], v[38:39], v[110:111]
	v_pk_mul_f32 v[34:35], v[34:35], v[114:115]
	v_pk_mul_f32 v[32:33], v[32:33], v[112:113]
	v_pk_mul_f32 v[60:61], v[60:61], v[100:101]
	v_pk_mul_f32 v[56:57], v[56:57], v[104:105]
	v_pk_mul_f32 v[52:53], v[52:53], v[108:109]
	v_pk_mul_f32 v[62:63], v[62:63], v[102:103]
	v_pk_mul_f32 v[58:59], v[58:59], v[106:107]
	v_pk_mul_f32 v[54:55], v[54:55], v[110:111]
	v_pk_mul_f32 v[50:51], v[50:51], v[114:115]
	v_pk_mul_f32 v[48:49], v[48:49], v[112:113]
	v_pk_mul_f32 v[76:77], v[76:77], v[100:101]
	v_pk_mul_f32 v[72:73], v[72:73], v[104:105]
	v_pk_mul_f32 v[68:69], v[68:69], v[108:109]
	v_pk_mul_f32 v[78:79], v[78:79], v[102:103]
	v_pk_mul_f32 v[74:75], v[74:75], v[106:107]
	v_pk_mul_f32 v[70:71], v[70:71], v[110:111]
	v_pk_mul_f32 v[66:67], v[66:67], v[114:115]
	v_pk_mul_f32 v[64:65], v[64:65], v[112:113]
.LBB0_303:
	s_add_i32 s0, s19, 0x2000
	s_cmpk_lg_i32 s19, 0x4000
	s_cselect_b32 s50, s0, 0
	s_lshl_b32 s0, s38, 1
	v_add_u32_e32 v215, s0, v248
	ds_read_b64_tr_b16 v[192:193], v215 offset:24576
	ds_read_b64_tr_b16 v[194:195], v215 offset:25088
	s_waitcnt lgkmcnt(9)
	v_mfma_f32_32x32x16_bf16 v[112:127], v[96:99], v[188:191], v[80:95]
	v_add_f32_e32 v100, v144, v145
	v_add_f32_e32 v100, v146, v100
	v_add_f32_e32 v100, v147, v100
	v_add_f32_e32 v100, v148, v100
	v_add_f32_e32 v100, v149, v100
	v_cvt_pk_bf16_f32 v180, v144, v145
	v_cvt_pk_bf16_f32 v181, v146, v147
	ds_read_b64_tr_b16 v[144:145], v215 offset:28672
	ds_read_b64_tr_b16 v[146:147], v215 offset:29184
	v_add_f32_e32 v96, v150, v100
	v_add_f32_e32 v96, v151, v96
	v_add_f32_e32 v96, v152, v96
	v_add_f32_e32 v160, v153, v96
	s_waitcnt lgkmcnt(10)
	v_mfma_f32_32x32x16_bf16 v[96:111], v[204:207], v[188:191], v[80:95]
	v_cvt_pk_bf16_f32 v182, v148, v149
	v_cvt_pk_bf16_f32 v183, v150, v151
	ds_read_b64_tr_b16 v[148:149], v215 offset:25600
	ds_read_b64_tr_b16 v[150:151], v215 offset:26112
	s_waitcnt lgkmcnt(11)
	v_mfma_f32_32x32x16_bf16 v[112:127], v[208:211], v[184:187], v[112:127]
	v_add_f32_e32 v160, v154, v160
	v_add_f32_e32 v160, v155, v160
	v_add_f32_e32 v160, v156, v160
	v_add_f32_e32 v160, v157, v160
	v_cvt_pk_bf16_f32 v172, v152, v153
	v_cvt_pk_bf16_f32 v173, v154, v155
	ds_read_b64_tr_b16 v[152:153], v215 offset:29696
	ds_read_b64_tr_b16 v[154:155], v215 offset:30208
	s_waitcnt lgkmcnt(12)
	v_mfma_f32_32x32x16_bf16 v[96:111], v[200:203], v[184:187], v[96:111]
	v_add_f32_e32 v160, v158, v160
	v_add_f32_e32 v160, v159, v160
	v_add_f32_e32 v160, v128, v160
	v_add_f32_e32 v160, v129, v160
	v_cvt_pk_bf16_f32 v174, v156, v157
	v_cvt_pk_bf16_f32 v175, v158, v159
	ds_read_b64_tr_b16 v[156:157], v215 offset:26624
	ds_read_b64_tr_b16 v[158:159], v215 offset:27136
	s_waitcnt lgkmcnt(13)
	v_mfma_f32_32x32x16_bf16 v[112:127], v[196:199], v[176:179], v[112:127]
	v_add_f32_e32 v160, v130, v160
	v_add_f32_e32 v160, v131, v160
	v_add_f32_e32 v160, v132, v160
	v_add_f32_e32 v160, v133, v160
	v_cvt_pk_bf16_f32 v164, v128, v129
	v_cvt_pk_bf16_f32 v165, v130, v131
	ds_read_b64_tr_b16 v[128:129], v215 offset:30720
	ds_read_b64_tr_b16 v[130:131], v215 offset:31232
	s_waitcnt lgkmcnt(14)
	v_mfma_f32_32x32x16_bf16 v[96:111], v[10:13], v[176:179], v[96:111]
	v_add_f32_e32 v10, v134, v160
	v_add_f32_e32 v10, v135, v10
	v_add_f32_e32 v10, v136, v10
	v_add_f32_e32 v160, v137, v10
	v_cvt_pk_bf16_f32 v166, v132, v133
	v_cvt_pk_bf16_f32 v167, v134, v135
	ds_read_b64_tr_b16 v[10:11], v215 offset:27648
	ds_read_b64_tr_b16 v[12:13], v215 offset:28160
	s_waitcnt lgkmcnt(14)
	v_mfma_f32_32x32x16_bf16 v[112:127], v[6:9], v[168:171], v[112:127]
	v_add_f32_e32 v6, v138, v160
	v_add_f32_e32 v6, v139, v6
	v_add_f32_e32 v6, v140, v6
	v_add_f32_e32 v132, v141, v6
	v_cvt_pk_bf16_f32 v160, v136, v137
	v_cvt_pk_bf16_f32 v161, v138, v139
	ds_read_b64_tr_b16 v[6:7], v215 offset:31744
	ds_read_b64_tr_b16 v[8:9], v215 offset:32256
	v_mfma_f32_32x32x16_bf16 v[96:111], v[2:5], v[168:171], v[96:111]
	v_add_f32_e32 v2, v142, v132
	v_add_f32_e32 v2, v143, v2
	v_add_f32_e32 v250, v214, v2
	v_cvt_pk_bf16_f32 v162, v140, v141
	v_cvt_pk_bf16_f32 v163, v142, v143
	s_add_i32 s0, s19, s46
	s_mov_b32 s1, m0
	s_mov_b32 m0, s0
	s_nop 0
	global_load_lds_dwordx4 v253, s[98:99]
	s_mov_b32 m0, s1
	s_waitcnt lgkmcnt(14)
	v_mfma_f32_32x32x16_bf16 v[16:31], v[180:183], v[192:195], v[16:31]
	v_max_f32_e32 v2, v112, v113
	v_max3_f32 v3, v114, v115, v97
	v_max3_f32 v2, v2, v96, v98
	v_max3_f32 v2, v2, v99, v116
	v_max3_f32 v3, v3, v118, v119
	v_max3_f32 v2, v2, v117, v100
	s_waitcnt lgkmcnt(12)
	v_mfma_f32_32x32x16_bf16 v[32:47], v[180:183], v[144:147], v[32:47]
	v_max3_f32 v3, v3, v102, v103
	v_max3_f32 v2, v2, v101, v120
	v_max3_f32 v3, v3, v122, v123
	v_max3_f32 v2, v2, v121, v104
	v_max3_f32 v3, v3, v106, v107
	v_max3_f32 v2, v2, v105, v124
	s_waitcnt lgkmcnt(10)
	v_mfma_f32_32x32x16_bf16 v[16:31], v[172:175], v[148:151], v[16:31]
	v_max3_f32 v3, v3, v126, v127
	v_max3_f32 v2, v2, v125, v108
	v_max3_f32 v3, v3, v110, v111
	v_max3_f32 v2, v2, v109, v3
	v_mov_b32_e32 v3, v2
	s_nop 1
	v_permlane32_swap_b32_e32 v2, v3
	v_max_f32_e32 v2, v2, v3
	v_cmp_lt_f32_e32 vcc, s25, v2
	s_cmp_lg_u64 vcc, 0
	s_cselect_b64 s[78:79], -1, 0
	s_cbranch_vccnz .LBB0_311
.LBB0_304:
	v_exp_f32_e32 v112, v112
	v_exp_f32_e32 v113, v113
	ds_read_b64_tr_b16 v[2:3], v215 offset:32768
	ds_read_b64_tr_b16 v[4:5], v215 offset:33280
	v_exp_f32_e32 v114, v114
	v_exp_f32_e32 v115, v115
	ds_read_b64_tr_b16 v[132:133], v215 offset:36864
	ds_read_b64_tr_b16 v[134:135], v215 offset:37376
	s_lshl_b32 s0, s50, 1
	s_add_i32 s18, s0, s47
	s_mov_b32 s0, m0
	s_mov_b32 m0, s18
	s_nop 0
	global_load_lds_dwordx4 v255, s[100:101]
	s_mov_b32 m0, s0
	v_exp_f32_e32 v116, v116
	v_exp_f32_e32 v117, v117
	ds_read_b64_tr_b16 v[136:137], v215 offset:33792
	ds_read_b64_tr_b16 v[138:139], v215 offset:34304
	s_add_i32 s0, s18, 0x1f80
	s_mov_b32 s1, m0
	s_mov_b32 m0, s0
	s_nop 0
	global_load_lds_dwordx4 v255, s[100:101] offset:128
	s_mov_b32 m0, s1
	s_add_u32 s98, s98, 0x20000
	s_addc_u32 s99, s99, 0
	s_add_u32 s100, s100, 0x20000
	s_addc_u32 s101, s101, 0
	s_waitcnt lgkmcnt(14)
	v_mfma_f32_32x32x16_bf16 v[32:47], v[172:175], v[152:155], v[32:47]
	v_exp_f32_e32 v118, v118
	v_exp_f32_e32 v119, v119
	ds_read_b64_tr_b16 v[140:141], v215 offset:37888
	ds_read_b64_tr_b16 v[142:143], v215 offset:38400
	s_waitcnt lgkmcnt(14)
	v_mfma_f32_32x32x16_bf16 v[16:31], v[164:167], v[156:159], v[16:31]
	v_exp_f32_e32 v120, v120
	v_exp_f32_e32 v121, v121
	ds_read_b64_tr_b16 v[144:145], v215 offset:34816
	ds_read_b64_tr_b16 v[146:147], v215 offset:35328
	s_waitcnt lgkmcnt(14)
	v_mfma_f32_32x32x16_bf16 v[32:47], v[164:167], v[128:131], v[32:47]
	v_exp_f32_e32 v122, v122
	v_exp_f32_e32 v123, v123
	ds_read_b64_tr_b16 v[128:129], v215 offset:38912
	ds_read_b64_tr_b16 v[130:131], v215 offset:39424
	s_waitcnt lgkmcnt(14)
	v_mfma_f32_32x32x16_bf16 v[16:31], v[160:163], v[10:13], v[16:31]
	v_exp_f32_e32 v124, v124
	v_exp_f32_e32 v125, v125
	ds_read_b64_tr_b16 v[10:11], v215 offset:35840
	ds_read_b64_tr_b16 v[12:13], v215 offset:36352
	s_waitcnt lgkmcnt(14)
	v_mfma_f32_32x32x16_bf16 v[32:47], v[160:163], v[6:9], v[32:47]
	v_exp_f32_e32 v126, v126
	v_exp_f32_e32 v127, v127
	ds_read_b64_tr_b16 v[6:7], v215 offset:39936
	ds_read_b64_tr_b16 v[8:9], v215 offset:40448
	s_waitcnt lgkmcnt(14)
	v_mfma_f32_32x32x16_bf16 v[48:63], v[180:183], v[2:5], v[48:63]
	v_exp_f32_e32 v96, v96
	v_exp_f32_e32 v97, v97
	s_waitcnt lgkmcnt(12)
	v_mfma_f32_32x32x16_bf16 v[64:79], v[180:183], v[132:135], v[64:79]
	v_exp_f32_e32 v98, v98
	v_exp_f32_e32 v99, v99
	v_add_u32_e32 v2, s50, v247
	ds_read_b128 v[220:223], v2
	ds_read_b128 v[216:219], v2 offset:512
	s_waitcnt lgkmcnt(12)
	v_mfma_f32_32x32x16_bf16 v[48:63], v[172:175], v[136:139], v[48:63]
	v_exp_f32_e32 v100, v100
	v_exp_f32_e32 v101, v101
	ds_read_b128 v[212:215], v2 offset:2048
	ds_read_b128 v[208:211], v2 offset:2560
	s_waitcnt lgkmcnt(12)
	v_mfma_f32_32x32x16_bf16 v[64:79], v[172:175], v[140:143], v[64:79]
	v_exp_f32_e32 v102, v102
	v_exp_f32_e32 v103, v103
	ds_read_b128 v[204:207], v2 offset:4096
	ds_read_b128 v[200:203], v2 offset:4608
	s_waitcnt lgkmcnt(12)
	v_mfma_f32_32x32x16_bf16 v[48:63], v[164:167], v[144:147], v[48:63]
	v_exp_f32_e32 v104, v104
	v_exp_f32_e32 v105, v105
	ds_read_b128 v[196:199], v2 offset:6144
	ds_read_b128 v[192:195], v2 offset:6656
	s_waitcnt lgkmcnt(12)
	v_mfma_f32_32x32x16_bf16 v[64:79], v[164:167], v[128:131], v[64:79]
	v_exp_f32_e32 v106, v106
	v_exp_f32_e32 v107, v107
	s_waitcnt lgkmcnt(10)
	v_mfma_f32_32x32x16_bf16 v[48:63], v[160:163], v[10:13], v[48:63]
	v_exp_f32_e32 v108, v108
	v_exp_f32_e32 v109, v109
	s_waitcnt lgkmcnt(8)
	v_mfma_f32_32x32x16_bf16 v[64:79], v[160:163], v[6:9], v[64:79]
	v_exp_f32_e32 v110, v110
	v_exp_f32_e32 v111, v111
	s_waitcnt vmcnt(3) lgkmcnt(0)
	s_barrier
	s_andn2_b64 vcc, exec, s[78:79]
	s_cbranch_vccnz .LBB0_306
	s_waitcnt lgkmcnt(0)
	ds_read_b128 v[2:5], v0 offset:96
	ds_read_b128 v[6:9], v0 offset:64
	ds_read_b128 v[10:13], v0 offset:32
	ds_read_b128 v[128:131], v0
	s_waitcnt lgkmcnt(3)
	v_pk_mul_f32 v[28:29], v[28:29], v[2:3]
	s_waitcnt lgkmcnt(2)
	v_pk_mul_f32 v[24:25], v[24:25], v[6:7]
	s_waitcnt lgkmcnt(1)
	v_pk_mul_f32 v[20:21], v[20:21], v[10:11]
	v_pk_mul_f32 v[30:31], v[30:31], v[4:5]
	v_pk_mul_f32 v[26:27], v[26:27], v[8:9]
	v_pk_mul_f32 v[22:23], v[22:23], v[12:13]
	s_waitcnt lgkmcnt(0)
	v_pk_mul_f32 v[18:19], v[18:19], v[130:131]
	v_pk_mul_f32 v[16:17], v[16:17], v[128:129]
	v_pk_mul_f32 v[44:45], v[44:45], v[2:3]
	v_pk_mul_f32 v[40:41], v[40:41], v[6:7]
	v_pk_mul_f32 v[36:37], v[36:37], v[10:11]
	v_pk_mul_f32 v[46:47], v[46:47], v[4:5]
	v_pk_mul_f32 v[42:43], v[42:43], v[8:9]
	v_pk_mul_f32 v[38:39], v[38:39], v[12:13]
	v_pk_mul_f32 v[34:35], v[34:35], v[130:131]
	v_pk_mul_f32 v[32:33], v[32:33], v[128:129]
	v_pk_mul_f32 v[60:61], v[60:61], v[2:3]
	v_pk_mul_f32 v[56:57], v[56:57], v[6:7]
	v_pk_mul_f32 v[52:53], v[52:53], v[10:11]
	v_pk_mul_f32 v[62:63], v[62:63], v[4:5]
	v_pk_mul_f32 v[58:59], v[58:59], v[8:9]
	v_pk_mul_f32 v[54:55], v[54:55], v[12:13]
	v_pk_mul_f32 v[50:51], v[50:51], v[130:131]
	v_pk_mul_f32 v[48:49], v[48:49], v[128:129]
	v_pk_mul_f32 v[76:77], v[76:77], v[2:3]
	v_pk_mul_f32 v[72:73], v[72:73], v[6:7]
	v_pk_mul_f32 v[68:69], v[68:69], v[10:11]
	v_pk_mul_f32 v[78:79], v[78:79], v[4:5]
	v_pk_mul_f32 v[74:75], v[74:75], v[8:9]
	v_pk_mul_f32 v[70:71], v[70:71], v[12:13]
	v_pk_mul_f32 v[66:67], v[66:67], v[130:131]
	v_pk_mul_f32 v[64:65], v[64:65], v[128:129]
